# half of the workgroups (blockIdx bit 3) run the attention mixers in the order A,B,C instead of C,A,B so that the weight-conversion bursts and the power draw of the C mixer are spread over the phase
# speedup vs baseline: 1.0061x; 1.0061x over previous
; #define LAS __attribute__((address_space(3)))
; __device__ __forceinline__ void attn_phase(CP P, LAS unsigned char* lds, int layer) {
;     const bf16_t* proj = (const bf16_t*)(P->ws + WS_PROJ); const bf16_t* vt = (const bf16_t*)(P->ws + WS_VT); bf16_t* obuf = (bf16_t*)(P->ws + WS_O);
;     const int G = gridDim.x;
;     unsigned long long* sgA = (unsigned long long*)(P->ws + WS_SG) + (size_t)(3 * layer) * MTOK; unsigned long long* sgB = sgA + MTOK; unsigned long long* sgC = sgB + MTOK;
;     {
;         float gq = 0.f, gk = 0.f;
;         for (int d = 0; d < 64; ++d) { gq = fmaxf(gq, fabsf(P->c_q_gain[layer * 64 + d])); gk = fmaxf(gk, fabsf(P->c_k_gain[layer * 64 + d])); }
;         const float bound = 64.f * C2 * gq * gk;
;         if (bound < 60.f) {
;             for (int u = blockIdx.x; u < 8 * 64; u += G) attn_c_unit(lds, proj, vt, obuf, (u & 7) >> 2, u & 3, u >> 3, 0.f, sgC);
;         } else {
;             for (int u = blockIdx.x; u < 8 * 128; u += G) attn_unit<2>(lds, proj, vt, obuf, (u & 7) >> 2, u & 3, u >> 3, nullptr, nullptr, sgC, false, P, -1, 0);
;         }
;     }
;     { int prev = -1; for (int u = blockIdx.x; u < 4 * 128; u += G) { attn_unit<0>(lds, proj, vt, obuf, (u & 3) >> 1, u & 1, u >> 2, P->t5, P->a_sink + layer * 8, sgA, (u & 1) != prev, P, layer, u * 16); prev = u & 1; } }
.LBB0_192:
	s_or_b64 exec, exec, s[4:5]
	v_readlane_b32 s8, v250, 11
	v_readlane_b32 s9, v250, 12
	s_waitcnt lgkmcnt(0)
	s_barrier
	s_bfe_u32 s4, s2, 0x10003
	s_nop 0
	v_writelane_b32 v250, s4, 52
.Lattn_pre:
	s_load_dwordx4 s[12:15], s[8:9], 0x30
	s_load_dwordx2 s[82:83], s[8:9], 0x88
	s_mov_b64 s[4:5], 0
	v_mov_b32_e32 v0, 0
	v_mov_b32_e32 v1, 0
	s_waitcnt lgkmcnt(0)
	s_add_u32 s6, s12, s72
	s_addc_u32 s7, s13, s73
	s_add_u32 s10, s14, s72
	s_addc_u32 s11, s15, s73
	v_and_b32_e32 v2, 63, v199
	v_lshlrev_b32_e32 v2, 2, v2
	global_load_dword v3, v2, s[6:7]
	global_load_dword v4, v2, s[10:11]
	s_waitcnt vmcnt(0)
	v_and_b32_e32 v3, 0x7fffffff, v3
	v_and_b32_e32 v4, 0x7fffffff, v4
	ds_swizzle_b32 v5, v3 offset:0x041f
	ds_swizzle_b32 v6, v4 offset:0x041f
	s_waitcnt lgkmcnt(0)
	v_max_f32_e32 v3, v3, v5
	v_max_f32_e32 v4, v4, v6
	ds_swizzle_b32 v5, v3 offset:0x081f
	ds_swizzle_b32 v6, v4 offset:0x081f
	s_waitcnt lgkmcnt(0)
	v_max_f32_e32 v3, v3, v5
	v_max_f32_e32 v4, v4, v6
	ds_swizzle_b32 v5, v3 offset:0x101f
	ds_swizzle_b32 v6, v4 offset:0x101f
	s_waitcnt lgkmcnt(0)
	v_max_f32_e32 v3, v3, v5
	v_max_f32_e32 v4, v4, v6
	ds_swizzle_b32 v5, v3 offset:0x201f
	ds_swizzle_b32 v6, v4 offset:0x201f
	s_waitcnt lgkmcnt(0)
	v_max_f32_e32 v3, v3, v5
	v_max_f32_e32 v4, v4, v6
	ds_swizzle_b32 v5, v3 offset:0x401f
	ds_swizzle_b32 v6, v4 offset:0x401f
	s_waitcnt lgkmcnt(0)
	v_max_f32_e32 v3, v3, v5
	v_max_f32_e32 v4, v4, v6
	s_nop 1
	v_readlane_b32 s4, v3, 0
	v_readlane_b32 s5, v3, 32
	v_readlane_b32 s12, v4, 0
	v_readlane_b32 s13, v4, 32
	s_nop 3
	v_mov_b32_e32 v1, s4
	v_mov_b32_e32 v0, s12
	v_max_f32_e32 v1, s5, v1
	v_max_f32_e32 v0, s13, v0
	s_mul_i32 s4, s74, 0x60000
	s_add_u32 s4, s82, s4
	s_addc_u32 s5, s83, 0
	s_add_u32 s38, s4, 0x2b120000
	s_addc_u32 s39, s5, 0
	s_add_u32 s84, s82, 0x21400000
	s_addc_u32 s85, s83, 0
	s_add_u32 s86, s82, 0x19c00000
	s_addc_u32 s87, s83, 0
	s_add_u32 s88, s82, 0x23000000
	s_addc_u32 s89, s83, 0
	v_mul_f32_e32 v1, 0x4138aa3b, v1
	s_add_u32 s20, s4, 0x2b160000
	v_mul_f32_e32 v0, v0, v1
	s_mov_b32 s4, 0x42700000
	v_cmp_ngt_f32_e32 vcc, s4, v0
	s_addc_u32 s21, s5, 0
	v_readlane_b32 s6, v250, 52
	s_nop 3
	s_cmp_eq_u32 s6, 1
	s_cbranch_scc0 .Lattn_c_entry
	s_mov_b64 s[4:5], -1
	s_branch .LBB0_218
.Lattn_c_entry:
	s_cbranch_vccz .LBB0_202
	v_readlane_b32 s4, v250, 5
	v_readlane_b32 s5, v250, 6
	s_andn2_b64 vcc, exec, s[4:5]
	s_cbranch_vccnz .LBB0_203
	s_add_u32 s4, s82, 0x21400080
	s_addc_u32 s5, s83, 0
	s_add_u32 s6, s82, 0x19c79a00
	s_addc_u32 s7, s83, 0
	s_mov_b32 s14, s2
	s_mov_b32 s15, s2
	s_branch .LBB0_198

; __device__ __forceinline__ void attn_phase(CP P, LAS unsigned char* lds, int layer) {
;     ...
;     { int prev = -1; for (int u = blockIdx.x; u < 4 * 128; u += G) { attn_unit<0>(lds, proj, vt, obuf, (u & 3) >> 1, u & 1, u >> 2, P->t5, P->a_sink + layer * 8, sgA, (u & 1) != prev, P, layer, u * 16); prev = u & 1; } }
;     { int prev = -1; for (int u = blockIdx.x; u < 16 * 32; u += G) { attn_b_unit(lds, proj, vt, obuf, (u & 15) >> 3, u & 7, u >> 4, P->b_rpb + (size_t)layer * 8 * 15 * 31, sgB, (u & 7) != prev, P, layer, (512 + u) * 16); prev = u & 7; } }
.LBB0_218:
	v_readlane_b32 s6, v250, 52
	s_nop 3
	s_cmp_eq_u32 s6, 2
	s_cbranch_scc1 .Lattn_end
	s_and_b64 vcc, exec, s[4:5]
	v_readlane_b32 s4, v250, 7
	v_readlane_b32 s5, v250, 8
	s_nop 1
	v_cndmask_b32_e64 v0, 0, 1, s[4:5]
	v_cmp_ne_u32_e64 s[4:5], 1, v0
	s_nop 1
	v_writelane_b32 v250, s4, 48
	s_nop 1
	v_writelane_b32 v250, s5, 49
	s_cbranch_vccz .LBB0_395
	v_readlane_b32 s4, v250, 48
	v_readlane_b32 s5, v250, 49
	s_and_b64 vcc, exec, s[4:5]
	s_cbranch_vccnz .LBB0_395
	s_load_dwordx4 s[12:15], s[8:9], 0x18
	s_lshl_b32 s54, s74, 3
	s_lshl_b64 s[6:7], s[54:55], 2
	s_mov_b32 s4, -1
	s_mov_b32 s44, s2
	s_waitcnt lgkmcnt(0)
	s_add_u32 s24, s12, s6
	s_addc_u32 s36, s13, s7
	s_cmp_lg_u32 s74, 3
	s_cselect_b64 s[12:13], -1, 0
	s_add_i32 s40, s74, 1
	s_add_u32 s41, s82, 0xdc00000
	s_addc_u32 s42, s83, 0
	s_add_u32 s43, s82, 0x5c00000
	s_addc_u32 s77, s83, 0
	s_add_u32 s79, s82, 0x3c00000
	s_addc_u32 s81, s83, 0
	s_branch .LBB0_222

; __device__ __forceinline__ void attn_phase(CP P, LAS unsigned char* lds, int layer) {
;     ...
;             for (int u = blockIdx.x; u < 8 * 64; u += G) attn_c_unit(lds, proj, vt, obuf, (u & 7) >> 2, u & 3, u >> 3, 0.f, sgC);
;         } else {
;             for (int u = blockIdx.x; u < 8 * 128; u += G) attn_unit<2>(lds, proj, vt, obuf, (u & 7) >> 2, u & 3, u >> 3, nullptr, nullptr, sgC, false, P, -1, 0);
;         }
;     }
;     { int prev = -1; for (int u = blockIdx.x; u < 4 * 128; u += G) { attn_unit<0>(lds, proj, vt, obuf, (u & 3) >> 1, u & 1, u >> 2, P->t5, P->a_sink + layer * 8, sgA, (u & 1) != prev, P, layer, u * 16); prev = u & 1; } }
;     { int prev = -1; for (int u = blockIdx.x; u < 16 * 32; u += G) { attn_b_unit(lds, proj, vt, obuf, (u & 15) >> 3, u & 7, u >> 4, P->b_rpb + (size_t)layer * 8 * 15 * 31, sgB, (u & 7) != prev, P, layer, (512 + u) * 16); prev = u & 7; } }
.LBB0_395:
	v_readlane_b32 s6, v250, 52
	s_nop 3
	s_cmp_eq_u32 s6, 1
	s_cbranch_scc0 .Lattn_end
	s_mov_b32 s6, 2
	s_nop 0
	v_writelane_b32 v250, s6, 52
	v_readlane_b32 s8, v250, 11
	v_readlane_b32 s9, v250, 12
	s_nop 3
	s_branch .Lattn_pre
